# stack13 + sample attention chunk loop VALU trims: row_bcast steps of the wave sum as v_add_f32_dpp, self-max folded, 16 dead SGPR reloads hoisted out of the chunk loop
# baseline (speedup 1.0000x reference)
; #define LAS __attribute__((address_space(3)))
; __device__ __forceinline__ void sattn_unit(const bf16* Qb, const bf16* Kb, const bf16* Vb, const float* ck, const float* cv, const int* pt, bf16* MIX, const float* sg, float lam,
;                                            int s, int h, int c0, LAS unsigned char* lds, int tid_in) {
;     int tid = tid_in; asm volatile("" : "+v"(tid));
;     const int lane = tid & 63, w = __builtin_amdgcn_readfirstlane(tid >> 6);
;     const float slope2 = exp2f(-2.f * (float)(h + 1)) * LOG2E;
;     LAS float* sc = (LAS float*)(lds + SA_SC) + w * 512;
;     LAS float* pl = (LAS float*)(lds + SA_PL) + w * 512;
;     LAS float* accm = (LAS float*)(lds + SA_ACC);
;     LAS float* ml = (LAS float*)(lds + SA_ML);
;     LAS float* fin = (LAS float*)(lds + SA_FIN);
;     const int r32 = lane & 31, hi = lane >> 5;
;     bf16x8 qf[2][4];
; #pragma unroll
;     for (int mp = 0; mp < 2; ++mp)
; #pragma unroll
;         for (int ks = 0; ks < 4; ++ks) qf[mp][ks] = *(const bf16x8*)(Qb + (size_t)(MP + 4 * s + (r32 & 3)) * 512 + h * 128 + mp * 64 + 16 * ks + 8 * hi);
;     float mrun[8], lrun[8], acc[8][4];
; #pragma unroll
;     for (int c = 0; c < 8; ++c) { mrun[c] = -INFINITY; lrun[c] = 0.f; acc[c][0] = 0.f; acc[c][1] = 0.f; acc[c][2] = 0.f; acc[c][3] = 0.f; }
;     for (int chunk = c0 + w; chunk < 32; chunk += 8) {
;         const int page = pt[s * NPAGES + (chunk >> 1)];
;         const size_t tok0 = (size_t)page * PAGE + (chunk & 1) * 64;
;         const int kp0 = 64 * chunk;
.LBB0_487:
	s_or_b64 exec, exec, s[0:1]
	s_waitcnt lgkmcnt(0)
	s_barrier
	ds_read_b32 v2, v148
	s_mov_b64 s[0:1], -1
	s_waitcnt lgkmcnt(0)
	v_readfirstlane_b32 s2, v2
	s_cmpk_gt_i32 s2, 0x1ff
	s_cbranch_scc1 .LBB0_482
	s_lshr_b32 s0, s2, 6
	s_and_b32 s0, s0, 6
	s_or_b32 s0, s0, -8
	v_ldexp_f32 v2, 1.0, s0
	v_mul_f32_e32 v151, 0x3fb8aa3b, v2
	v_div_scale_f32 v2, s[0:1], v151, v151, v1
	v_rcp_f32_e32 v3, v2
	v_div_scale_f32 v4, vcc, v1, v151, v1
	s_and_b32 s18, s2, 0x7f
	v_fma_f32 v5, -v2, v3, 1.0
	v_fmac_f32_e32 v3, v5, v3
	v_mul_f32_e32 v5, v4, v3
	v_fma_f32 v6, -v2, v5, v4
	v_fmac_f32_e32 v5, v6, v3
	v_fma_f32 v2, -v2, v5, v4
	v_div_fmas_f32 v2, v2, v3, v5
	v_div_fixup_f32 v2, v2, v151, v1
	v_add_f32_e32 v2, 1.0, v2
	v_min_f32_e32 v2, 0x49742400, v2
	v_cvt_i32_f32_e32 v3, v2
	v_mov_b32_e32 v2, v0
	s_lshl_b32 s16, s18, 11
	v_sub_u32_e32 v3, 0x800, v3
	v_ashrrev_i32_e32 v3, 6, v3
	v_max_i32_e32 v3, 0, v3
	v_readfirstlane_b32 s19, v2
	v_readfirstlane_b32 s0, v3
	s_ashr_i32 s8, s19, 6
	s_lshl_b32 s9, s8, 9
	s_andn2_b32 s17, 0x180, s2
	v_and_b32_e32 v138, 31, v2
	s_add_i32 s20, s8, s0
	v_and_b32_e32 v150, 63, v2
	v_bfe_u32 v134, v2, 5, 1
	s_cmp_gt_i32 s20, 31
	v_lshlrev_b32_e32 v136, 4, v138
	s_cbranch_scc1 .LBB0_502
	v_lshlrev_b32_e32 v2, 9, v2
	v_and_b32_e32 v2, 0x600, v2
	v_or_b32_e32 v2, s16, v2
	v_lshlrev_b32_e32 v130, 1, v2
	v_lshl_add_u64 v[2:3], s[4:5], 0, v[130:131]
	s_lshl_b32 s6, s17, 1
	v_lshl_add_u64 v[2:3], v[2:3], 0, s[6:7]
	v_lshlrev_b32_e32 v130, 4, v134
	v_lshl_add_u64 v[2:3], v[2:3], 0, v[130:131]
	s_mov_b64 s[0:1], 0x1000000
	v_lshl_add_u64 v[4:5], v[2:3], 0, s[0:1]
	s_mov_b32 s0, 0x1000000
	v_add_co_u32_e32 v2, vcc, s0, v2
	v_readlane_b32 s52, v254, 10
	s_nop 0
	v_addc_co_u32_e32 v3, vcc, 0, v3, vcc
	global_load_dwordx4 v[18:21], v[4:5], off offset:32
	global_load_dwordx4 v[22:25], v[4:5], off offset:64
	global_load_dwordx4 v[26:29], v[4:5], off offset:96
	global_load_dwordx4 v[30:33], v[4:5], off offset:128
	global_load_dwordx4 v[34:37], v[4:5], off offset:160
	global_load_dwordx4 v[38:41], v[4:5], off offset:192
	global_load_dwordx4 v[42:45], v[2:3], off
	global_load_dwordx4 v[46:49], v[4:5], off offset:224
	s_lshl_b32 s0, s9, 2
	v_readlane_b32 s58, v254, 16
	v_readlane_b32 s59, v254, 17
	s_add_i32 s21, s0, 0
	s_lshl_b32 s22, s18, 4
	s_lshl_b32 s6, s17, 2
	s_mov_b64 s[50:51], s[58:59]
	v_readlane_b32 s53, v254, 11
	v_readlane_b32 s54, v254, 12
	v_readlane_b32 s55, v254, 13
	v_readlane_b32 s60, v254, 18
	v_readlane_b32 s61, v254, 19
	s_add_u32 s0, s50, s6
	v_readlane_b32 s62, v254, 20
	v_readlane_b32 s63, v254, 21
	s_mov_b64 s[52:53], s[60:61]
	s_addc_u32 s1, s51, 0
	v_lshlrev_b32_e32 v2, 5, v134
	v_mov_b32_e32 v3, v131
	v_lshl_add_u64 v[140:141], s[0:1], 0, v[2:3]
	s_add_u32 s0, s52, s6
	v_lshl_add_u32 v2, v138, 8, s21
	v_lshlrev_b32_e32 v3, 5, v150
	s_addc_u32 s1, s53, 0
	v_mov_b32_e32 v137, v131
	v_cmp_gt_u32_e64 s[2:3], 4, v138
	v_lshl_add_u32 v152, v150, 2, s21
	v_lshl_add_u64 v[142:143], s[0:1], 0, v[136:137]
	v_or_b32_e32 v144, 32, v138
	s_mov_b32 s25, 0xff800000
	v_mov_b32_e32 v85, 0
	v_mov_b32_e32 v84, 0
	v_mov_b32_e32 v83, 0
	v_mov_b32_e32 v82, 0
	v_mov_b32_e32 v89, 0
	v_mov_b32_e32 v88, 0
	v_mov_b32_e32 v87, 0
	v_mov_b32_e32 v86, 0
	v_mov_b32_e32 v50, 0
	v_mov_b32_e32 v51, 0
	v_mov_b32_e32 v54, 0
	v_mov_b32_e32 v55, 0
	v_mov_b32_e32 v52, 0
	v_mov_b32_e32 v53, 0
	v_mov_b32_e32 v56, 0
	v_mov_b32_e32 v57, 0
	v_mov_b32_e32 v58, 0
	v_mov_b32_e32 v59, 0
	v_mov_b32_e32 v62, 0
	v_mov_b32_e32 v63, 0
	v_mov_b32_e32 v60, 0
	v_mov_b32_e32 v61, 0
	v_mov_b32_e32 v64, 0
	v_mov_b32_e32 v65, 0
	v_mov_b32_e32 v66, 0
	v_mov_b32_e32 v67, 0
	v_mov_b32_e32 v74, 0
	v_mov_b32_e32 v75, 0
	v_mov_b32_e32 v68, 0
	v_mov_b32_e32 v69, 0
	v_mov_b32_e32 v76, 0
	v_mov_b32_e32 v77, 0
	v_mov_b32_e32 v78, 0
	v_mov_b32_e32 v79, 0
	v_mov_b32_e32 v70, 0
	v_mov_b32_e32 v71, 0
	v_mov_b32_e32 v80, 0
	v_mov_b32_e32 v81, 0
	v_mov_b32_e32 v72, 0
	v_mov_b32_e32 v73, 0
	v_add_u32_e32 v137, s21, v3
	v_add_u32_e32 v130, v2, v130
	s_mov_b32 s26, 0xff800000
	s_mov_b32 s29, 0xff800000
	s_mov_b32 s30, 0xff800000
	s_mov_b32 s35, 0xff800000
	s_mov_b32 s42, 0xff800000
	s_mov_b32 s44, 0xff800000
	s_mov_b32 s6, 0xff800000
	v_readlane_b32 s56, v254, 14
	v_readlane_b32 s57, v254, 15
	v_readlane_b32 s64, v254, 22
	v_readlane_b32 s65, v254, 23
	v_readlane_b32 s66, v254, 24
	v_readlane_b32 s67, v254, 25
	s_mov_b64 s[54:55], s[62:63]
	v_and_b32_e32 v246, 15, v252
	v_add_lshl_u32 v246, v246, s22, 2
	global_load_dword v246, v246, s[62:63]
	v_readlane_b32 s52, v254, 10
	v_readlane_b32 s62, v254, 20
	v_readlane_b32 s63, v254, 21
	v_readlane_b32 s53, v254, 11
	v_readlane_b32 s54, v254, 12
	v_readlane_b32 s55, v254, 13
	v_readlane_b32 s56, v254, 14
	v_readlane_b32 s57, v254, 15
	v_readlane_b32 s58, v254, 16
	v_readlane_b32 s59, v254, 17
	v_readlane_b32 s60, v254, 18
	v_readlane_b32 s61, v254, 19
	v_readlane_b32 s64, v254, 22
	v_readlane_b32 s65, v254, 23
	v_readlane_b32 s66, v254, 24
	v_readlane_b32 s67, v254, 25
; __device__ __forceinline__ u32x4 pack8(const f32x4 a, const f32x4 b) { u32x4 w; w.x = cvt_pk_bf16(a[0], a[1]); w.y = cvt_pk_bf16(a[2], a[3]); w.z = cvt_pk_bf16(b[0], b[1]); w.w = cvt_pk_bf16(b[2], b[3]); return w; }
; __device__ __forceinline__ void sattn_unit(const bf16* Qb, const bf16* Kb, const bf16* Vb, const float* ck, const float* cv, const int* pt, bf16* MIX, const float* sg, float lam,
;                                            int s, int h, int c0, LAS unsigned char* lds, int tid_in) {
;     ...
;         const int page = pt[s * NPAGES + (chunk >> 1)];
;         const size_t tok0 = (size_t)page * PAGE + (chunk & 1) * 64;
;         const int kp0 = 64 * chunk;
; #pragma unroll
;         for (int mp = 0; mp < 2; ++mp) {
;             f32x4 kk[2][4][2];
; #pragma unroll
;             for (int kb = 0; kb < 2; ++kb)
; #pragma unroll
;                 for (int ks = 0; ks < 4; ++ks) { const float* kp = ck + ((tok0 + kb * 32 + r32) * NH + h) * 128 + mp * 64 + 16 * ks + 8 * hi;
;                     kk[kb][ks][0] = *(const f32x4*)kp; kk[kb][ks][1] = *(const f32x4*)(kp + 4); }
;             asm volatile("s_waitcnt vmcnt(0)" ::: "memory");
; #pragma unroll
;             for (int kb = 0; kb < 2; ++kb) { f32x16 sa = {};
; #pragma unroll
;                 for (int ks = 0; ks < 4; ++ks) { const u32x4 kw = ep::pack8(kk[kb][ks][0], kk[kb][ks][1]);
;                     sa = __builtin_amdgcn_mfma_f32_32x32x16_bf16(__builtin_bit_cast(bf16x8, kw), qf[mp][ks], sa, 0, 0, 0); }
;                 if (r32 < 4) {
; #pragma unroll
;                     for (int r = 0; r < 16; ++r) sc[(mp * 4 + r32) * 64 + kb * 32 + (r & 3) + 8 * (r >> 2) + 4 * hi] = sa[r]; } }
.LBB0_490:
	s_ashr_i32 s0, s20, 1
	s_waitcnt vmcnt(0)
	v_readlane_b32 s1, v246, s0
	s_lshl_b32 s23, s20, 6
	s_and_b32 s0, s23, 64
	v_mov_b32_e32 v2, s1
	v_ashrrev_i32_e32 v3, 31, v2
	v_lshlrev_b64 v[122:123], 7, v[2:3]
	v_or_b32_e32 v128, s0, v122
	v_or_b32_e32 v122, v128, v138
	v_lshlrev_b64 v[2:3], 11, v[122:123]
	v_lshl_add_u64 v[124:125], v[140:141], 0, v[2:3]
	global_load_dwordx4 v[2:5], v[124:125], off offset:16
	global_load_dwordx4 v[6:9], v[124:125], off
	global_load_dwordx4 v[154:157], v[124:125], off offset:80
	global_load_dwordx4 v[158:161], v[124:125], off offset:64
	global_load_dwordx4 v[162:165], v[124:125], off offset:144
	global_load_dwordx4 v[166:169], v[124:125], off offset:128
	global_load_dwordx4 v[170:173], v[124:125], off offset:208
	global_load_dwordx4 v[174:177], v[124:125], off offset:192
	v_or_b32_e32 v122, v128, v144
	v_lshlrev_b64 v[10:11], 11, v[122:123]
	v_lshl_add_u64 v[126:127], v[140:141], 0, v[10:11]
	global_load_dwordx4 v[114:117], v[126:127], off offset:16
	global_load_dwordx4 v[118:121], v[126:127], off
	global_load_dwordx4 v[106:109], v[126:127], off offset:80
	global_load_dwordx4 v[110:113], v[126:127], off offset:64
	global_load_dwordx4 v[98:101], v[126:127], off offset:144
	global_load_dwordx4 v[102:105], v[126:127], off offset:128
	global_load_dwordx4 v[90:93], v[126:127], off offset:208
	global_load_dwordx4 v[94:97], v[126:127], off offset:192
	global_load_dwordx4 v[178:181], v[124:125], off offset:272
	global_load_dwordx4 v[182:185], v[124:125], off offset:256
	global_load_dwordx4 v[186:189], v[124:125], off offset:336
	global_load_dwordx4 v[190:193], v[124:125], off offset:320
	global_load_dwordx4 v[194:197], v[124:125], off offset:400
	global_load_dwordx4 v[198:201], v[124:125], off offset:384
	global_load_dwordx4 v[202:205], v[124:125], off offset:464
	global_load_dwordx4 v[206:209], v[124:125], off offset:448
	global_load_dwordx4 v[210:213], v[126:127], off offset:272
	global_load_dwordx4 v[214:217], v[126:127], off offset:256
	global_load_dwordx4 v[218:221], v[126:127], off offset:336
	global_load_dwordx4 v[222:225], v[126:127], off offset:320
	global_load_dwordx4 v[226:229], v[126:127], off offset:400
	global_load_dwordx4 v[230:233], v[126:127], off offset:384
	global_load_dwordx4 v[234:237], v[126:127], off offset:464
	global_load_dwordx4 v[242:245], v[126:127], off offset:448
	s_waitcnt vmcnt(16)
	s_waitcnt vmcnt(30)
	v_cvt_pk_bf16_f32 v6, v6, v7
	v_cvt_pk_bf16_f32 v7, v8, v9
	v_cvt_pk_bf16_f32 v8, v2, v3
	v_cvt_pk_bf16_f32 v9, v4, v5
	s_waitcnt vmcnt(28)
	v_cvt_pk_bf16_f32 v158, v158, v159
	v_cvt_pk_bf16_f32 v159, v160, v161
	v_mfma_f32_32x32x16_bf16 v[2:17], v[6:9], v[42:45], 0
	v_cvt_pk_bf16_f32 v160, v154, v155
	v_cvt_pk_bf16_f32 v161, v156, v157
	s_waitcnt vmcnt(26)
	v_cvt_pk_bf16_f32 v154, v166, v167
	v_cvt_pk_bf16_f32 v155, v168, v169
	v_cvt_pk_bf16_f32 v156, v162, v163
	v_cvt_pk_bf16_f32 v157, v164, v165
	v_mfma_f32_32x32x16_bf16 v[2:17], v[158:161], v[18:21], v[2:17]
	s_nop 0
	v_mfma_f32_32x32x16_bf16 v[2:17], v[154:157], v[22:25], v[2:17]
	s_waitcnt vmcnt(24)
	v_cvt_pk_bf16_f32 v154, v174, v175
	v_cvt_pk_bf16_f32 v155, v176, v177
	v_cvt_pk_bf16_f32 v156, v170, v171
	v_cvt_pk_bf16_f32 v157, v172, v173
	s_nop 1
	v_mfma_f32_32x32x16_bf16 v[2:17], v[154:157], v[26:29], v[2:17]
	s_and_saveexec_b64 s[0:1], s[2:3]
	s_cbranch_execz .LBB0_492
	s_nop 9
	ds_write_b128 v130, v[2:5]
	ds_write_b128 v130, v[6:9] offset:32
	ds_write_b128 v130, v[10:13] offset:64
	ds_write_b128 v130, v[14:17] offset:96

; #define DPP_F(old, x, ctrl, rmask, bc) __builtin_bit_cast(float, __builtin_amdgcn_update_dpp(__builtin_bit_cast(int, (old)), __builtin_bit_cast(int, (x)), (ctrl), (rmask), 0xf, (bc)))
; #define LDS_WAIT() asm volatile("s_waitcnt lgkmcnt(0)" ::: "memory")
; __device__ __forceinline__ float wave_sum(float v) {
;     v += DPP_F(0.f, v, 0x111, 0xf, true); v += DPP_F(0.f, v, 0x112, 0xf, true); v += DPP_F(0.f, v, 0x114, 0xf, true); v += DPP_F(0.f, v, 0x118, 0xf, true);
;     v += DPP_F(0.f, v, 0x142, 0xa, false); v += DPP_F(0.f, v, 0x143, 0xc, false);
;     return __builtin_bit_cast(float, __builtin_amdgcn_readlane(__builtin_bit_cast(int, v), 63));
; }
; __device__ __forceinline__ float wave_max(float v) {
;     v = fmaxf(v, DPP_F(v, v, 0x111, 0xf, false)); v = fmaxf(v, DPP_F(v, v, 0x112, 0xf, false)); v = fmaxf(v, DPP_F(v, v, 0x114, 0xf, false)); v = fmaxf(v, DPP_F(v, v, 0x118, 0xf, false));
;     v = fmaxf(v, DPP_F(v, v, 0x142, 0xa, false)); v = fmaxf(v, DPP_F(v, v, 0x143, 0xc, false));
;     return __builtin_bit_cast(float, __builtin_amdgcn_readlane(__builtin_bit_cast(int, v), 63));
; }
; __device__ __forceinline__ void sattn_unit(const bf16* Qb, const bf16* Kb, const bf16* Vb, const float* ck, const float* cv, const int* pt, bf16* MIX, const float* sg, float lam,
;                                            int s, int h, int c0, LAS unsigned char* lds, int tid_in) {
;     ...
;         for (int c = 0; c < 8; ++c) { const int t = c & 3;
;             const float sv = sc[c * 64 + lane] - slope2 * (float)(PAST + t - (kp0 + lane));
;             const float mn = __builtin_bit_cast(float, __builtin_amdgcn_readfirstlane(__builtin_bit_cast(int, fmaxf(mrun[c], wave_max(sv))))); const float p = __builtin_amdgcn_exp2f(sv - mn);
;             const float fsc_ = __builtin_amdgcn_exp2f(mrun[c] - mn); lrun[c] = __builtin_bit_cast(float, __builtin_amdgcn_readfirstlane(__builtin_bit_cast(int, lrun[c] * fsc_ + wave_sum(p)))); mrun[c] = mn; pl[lane * 8 + c] = p; acc[c][0] *= fsc_; acc[c][1] *= fsc_; acc[c][2] *= fsc_; acc[c][3] *= fsc_; }
;         LDS_WAIT(); asm volatile("" ::: "memory");
;         const float* vp = cv + ((tok0 + hi) * NH + h) * 128 + 4 * r32;
; #pragma unroll 1
;         for (int k0 = 0; k0 < 64; k0 += 32) { f32x4 vv[16];
; #pragma unroll
;             for (int k = 0; k < 16; ++k) vv[k] = *(const f32x4*)(vp + (size_t)(k0 + 2 * k) * NH * 128);
.LBB0_498:
	s_or_b64 exec, exec, s[0:1]
	s_waitcnt lgkmcnt(0)
	s_nop 8
	v_or_b32_e32 v213, s23, v150
	ds_read2st64_b32 v[210:211], v152 offset1:1
	v_sub_u32_e32 v212, 0x800, v213
	v_cvt_f32_u32_e32 v216, v212
	s_waitcnt lgkmcnt(0)
	v_fma_f32 v210, -v151, v216, v210
	v_mov_b32_e32 v212, v210
	v_or_b32_e32 v122, v128, v134
	v_lshlrev_b64 v[240:241], 11, v[122:123]
	v_lshl_add_u64 v[146:147], v[142:143], 0, v[240:241]
	v_mov_b32_e32 v106, v146
	v_mov_b32_e32 v107, v147
	s_movk_i32 s0, 0x2000
	v_add_co_u32_e64 v2, s[0:1], s0, v106
	global_load_dwordx4 v[110:113], v[106:107], off
	s_nop 0
	v_addc_co_u32_e64 v3, s[0:1], 0, v107, s[0:1]
	s_movk_i32 s0, 0x4000
	global_load_dwordx4 v[114:117], v[2:3], off offset:-4096
	global_load_dwordx4 v[118:121], v[2:3], off
	v_add_co_u32_e64 v2, s[0:1], s0, v106
	s_nop 0
	s_nop 0
	v_addc_co_u32_e64 v3, s[0:1], 0, v107, s[0:1]
	global_load_dwordx4 v[122:125], v[2:3], off offset:-4096
	global_load_dwordx4 v[126:129], v[2:3], off
	s_movk_i32 s0, 0x6000
	v_add_co_u32_e64 v6, s[0:1], s0, v106
	s_nop 0
	s_nop 0
	v_addc_co_u32_e64 v7, s[0:1], 0, v107, s[0:1]
	s_mov_b32 s0, 0x8000
	s_nop 0
	v_add_co_u32_e64 v14, s[0:1], s0, v106
	global_load_dwordx4 v[2:5], v[6:7], off offset:-4096
	s_nop 0
	global_load_dwordx4 v[6:9], v[6:7], off
	v_addc_co_u32_e64 v15, s[0:1], 0, v107, s[0:1]
	s_mov_b32 s0, 0xa000
	s_nop 0
	v_add_co_u32_e64 v248, s[0:1], s0, v106
	global_load_dwordx4 v[10:13], v[14:15], off offset:-4096
	s_nop 0
	global_load_dwordx4 v[14:17], v[14:15], off
	v_addc_co_u32_e64 v249, s[0:1], 0, v107, s[0:1]
	s_mov_b32 s0, 0xc000
	s_nop 0
	v_add_co_u32_e64 v94, s[0:1], s0, v106
	global_load_dwordx4 v[242:245], v[248:249], off offset:-4096
	s_nop 0
	global_load_dwordx4 v[248:251], v[248:249], off
	v_addc_co_u32_e64 v95, s[0:1], 0, v107, s[0:1]
	s_mov_b32 s0, 0xe000
	s_nop 0
	v_add_co_u32_e64 v102, s[0:1], s0, v106
	global_load_dwordx4 v[90:93], v[94:95], off offset:-4096
	s_nop 0
	global_load_dwordx4 v[94:97], v[94:95], off
	v_addc_co_u32_e64 v103, s[0:1], 0, v107, s[0:1]
	s_mov_b32 s0, 0xf000
	s_nop 0
	v_add_co_u32_e64 v106, s[0:1], s0, v106
	global_load_dwordx4 v[98:101], v[102:103], off offset:-4096
	s_nop 0
	global_load_dwordx4 v[102:105], v[102:103], off
	v_addc_co_u32_e64 v107, s[0:1], 0, v107, s[0:1]
	global_load_dwordx4 v[106:109], v[106:107], off
	v_max_f32_dpp v212, v210, v210 row_shr:1 row_mask:0xf bank_mask:0xf
	v_mov_b32_e32 v158, 0
	s_nop 0
	v_max_f32_dpp v212, v212, v212 row_shr:2 row_mask:0xf bank_mask:0xf
	v_mov_b32_e32 v160, 0
	v_mov_b32_e32 v162, 0
	v_max_f32_dpp v212, v212, v212 row_shr:4 row_mask:0xf bank_mask:0xf
	v_mov_b32_e32 v164, 0
	v_mov_b32_e32 v166, 0
	v_max_f32_dpp v212, v212, v212 row_shr:8 row_mask:0xf bank_mask:0xf
	v_mov_b32_e32 v168, 0
	s_mov_b32 s46, 0
	v_max_f32_dpp v212, v212, v212 row_bcast:15 row_mask:0xa bank_mask:0xf
	s_nop 1
	v_max_f32_dpp v212, v212, v212 row_bcast:31 row_mask:0xc bank_mask:0xf
	v_max_f32_e64 v214, s25, s25
	v_readlane_b32 s0, v212, 63
	s_nop 1
	v_max_f32_e32 v212, s0, v214
	s_nop 0
	v_readfirstlane_b32 s23, v212
	s_nop 1
	v_subrev_f32_e32 v210, s23, v210
	v_exp_f32_e32 v210, v210
	v_mov_b32_e32 v212, s23
	v_sub_f32_e32 v212, s25, v212
	v_exp_f32_e32 v212, v212
	v_add_f32_dpp v215, v210, v210 row_shr:1 row_mask:0xf bank_mask:0xf bound_ctrl:1
	v_mul_f32_e32 v214, v86, v212
	s_nop 0
	v_add_f32_dpp v215, v215, v215 row_shr:2 row_mask:0xf bank_mask:0xf bound_ctrl:1
	v_pk_mul_f32 v[50:51], v[50:51], v[212:213] op_sel_hi:[1,0]
	v_pk_mul_f32 v[52:53], v[52:53], v[212:213] op_sel_hi:[1,0]
	v_add_f32_dpp v215, v215, v215 row_shr:4 row_mask:0xf bank_mask:0xf bound_ctrl:1
	v_sub_u32_e32 v212, 0x801, v213
	v_readfirstlane_b32 s25, v214
	v_add_f32_dpp v215, v215, v215 row_shr:8 row_mask:0xf bank_mask:0xf bound_ctrl:1
	s_nop 1
	v_add_f32_dpp v153, v215, v215 row_bcast:15 row_mask:0xa bank_mask:0xf
	v_cvt_f32_u32_e32 v217, v212
	v_fma_f32 v211, -v151, v217, v211
	v_mov_b32_e32 v212, v211
	v_add_f32_dpp v153, v153, v153 row_bcast:31 row_mask:0xc bank_mask:0xf
	s_nop 0
	v_max_f32_dpp v212, v211, v211 row_shr:1 row_mask:0xf bank_mask:0xf
	s_nop 1
	v_max_f32_dpp v212, v212, v212 row_shr:2 row_mask:0xf bank_mask:0xf
	s_nop 1
	v_max_f32_dpp v212, v212, v212 row_shr:4 row_mask:0xf bank_mask:0xf
	s_nop 1
	v_max_f32_dpp v212, v212, v212 row_shr:8 row_mask:0xf bank_mask:0xf
	s_nop 1
	v_max_f32_dpp v212, v212, v212 row_bcast:15 row_mask:0xa bank_mask:0xf
	s_nop 1
	v_max_f32_dpp v212, v212, v212 row_bcast:31 row_mask:0xc bank_mask:0xf
	v_max_f32_e64 v214, s26, s26
	v_readlane_b32 s0, v212, 63
	s_nop 1
	v_max_f32_e32 v212, s0, v214
	s_nop 0
	v_readfirstlane_b32 s24, v212
	s_nop 1
	v_subrev_f32_e32 v211, s24, v211
	v_exp_f32_e32 v211, v211
	v_mov_b32_e32 v212, s24
	v_sub_f32_e32 v212, s26, v212
	v_exp_f32_e32 v212, v212
	v_add_f32_dpp v215, v211, v211 row_shr:1 row_mask:0xf bank_mask:0xf bound_ctrl:1
	v_mul_f32_e32 v214, v87, v212
	s_nop 0
	v_add_f32_dpp v215, v215, v215 row_shr:2 row_mask:0xf bank_mask:0xf bound_ctrl:1
	v_pk_mul_f32 v[58:59], v[58:59], v[212:213] op_sel_hi:[1,0]
	v_pk_mul_f32 v[60:61], v[60:61], v[212:213] op_sel_hi:[1,0]
	v_add_f32_dpp v215, v215, v215 row_shr:4 row_mask:0xf bank_mask:0xf bound_ctrl:1
	v_sub_u32_e32 v212, 0x802, v213
	v_readfirstlane_b32 s26, v214
	v_add_f32_dpp v215, v215, v215 row_shr:8 row_mask:0xf bank_mask:0xf bound_ctrl:1
	v_sub_u32_e32 v213, 0x803, v213
	s_nop 0
	v_add_f32_dpp v155, v215, v215 row_bcast:15 row_mask:0xa bank_mask:0xf
	ds_read2st64_b32 v[218:219], v152 offset0:2 offset1:3
	v_cvt_f32_u32_e32 v215, v212
	v_add_f32_dpp v155, v155, v155 row_bcast:31 row_mask:0xc bank_mask:0xf
	s_waitcnt lgkmcnt(0)
; #define DPP_F(old, x, ctrl, rmask, bc) __builtin_bit_cast(float, __builtin_amdgcn_update_dpp(__builtin_bit_cast(int, (old)), __builtin_bit_cast(int, (x)), (ctrl), (rmask), 0xf, (bc)))
; __device__ __forceinline__ float wave_sum(float v) {
;     v += DPP_F(0.f, v, 0x111, 0xf, true); v += DPP_F(0.f, v, 0x112, 0xf, true); v += DPP_F(0.f, v, 0x114, 0xf, true); v += DPP_F(0.f, v, 0x118, 0xf, true);
;     v += DPP_F(0.f, v, 0x142, 0xa, false); v += DPP_F(0.f, v, 0x143, 0xc, false);
;     return __builtin_bit_cast(float, __builtin_amdgcn_readlane(__builtin_bit_cast(int, v), 63));
; }
; __device__ __forceinline__ float wave_max(float v) {
;     v = fmaxf(v, DPP_F(v, v, 0x111, 0xf, false)); v = fmaxf(v, DPP_F(v, v, 0x112, 0xf, false)); v = fmaxf(v, DPP_F(v, v, 0x114, 0xf, false)); v = fmaxf(v, DPP_F(v, v, 0x118, 0xf, false));
;     v = fmaxf(v, DPP_F(v, v, 0x142, 0xa, false)); v = fmaxf(v, DPP_F(v, v, 0x143, 0xc, false));
;     return __builtin_bit_cast(float, __builtin_amdgcn_readlane(__builtin_bit_cast(int, v), 63));
; }
; __device__ __forceinline__ void sattn_unit(const bf16* Qb, const bf16* Kb, const bf16* Vb, const float* ck, const float* cv, const int* pt, bf16* MIX, const float* sg, float lam,
;                                            int s, int h, int c0, LAS unsigned char* lds, int tid_in) {
;     ...
;         for (int c = 0; c < 8; ++c) { const int t = c & 3;
;             const float sv = sc[c * 64 + lane] - slope2 * (float)(PAST + t - (kp0 + lane));
;             const float mn = __builtin_bit_cast(float, __builtin_amdgcn_readfirstlane(__builtin_bit_cast(int, fmaxf(mrun[c], wave_max(sv))))); const float p = __builtin_amdgcn_exp2f(sv - mn);
;             const float fsc_ = __builtin_amdgcn_exp2f(mrun[c] - mn); lrun[c] = __builtin_bit_cast(float, __builtin_amdgcn_readfirstlane(__builtin_bit_cast(int, lrun[c] * fsc_ + wave_sum(p)))); mrun[c] = mn; pl[lane * 8 + c] = p; acc[c][0] *= fsc_; acc[c][1] *= fsc_; acc[c][2] *= fsc_; acc[c][3] *= fsc_; }
	v_fma_f32 v212, -v151, v215, v218
	v_mov_b32_e32 v214, v212
	s_nop 1
	v_max_f32_dpp v214, v212, v212 row_shr:1 row_mask:0xf bank_mask:0xf
	s_nop 1
	v_max_f32_dpp v214, v214, v214 row_shr:2 row_mask:0xf bank_mask:0xf
	s_nop 1
	v_max_f32_dpp v214, v214, v214 row_shr:4 row_mask:0xf bank_mask:0xf
	s_nop 1
	v_max_f32_dpp v214, v214, v214 row_shr:8 row_mask:0xf bank_mask:0xf
	s_nop 1
	v_max_f32_dpp v214, v214, v214 row_bcast:15 row_mask:0xa bank_mask:0xf
	s_nop 1
	v_max_f32_dpp v214, v214, v214 row_bcast:31 row_mask:0xc bank_mask:0xf
	v_max_f32_e64 v218, s29, s29
	v_readlane_b32 s0, v214, 63
	s_nop 1
	v_max_f32_e32 v214, s0, v218
	s_nop 0
	v_readfirstlane_b32 s27, v214
	s_nop 1
	v_mov_b32_e32 v214, s27
	v_sub_f32_e32 v214, s29, v214
	v_exp_f32_e32 v214, v214
	v_subrev_f32_e32 v212, s27, v212
	v_exp_f32_e32 v212, v212
	v_mul_f32_e32 v218, v88, v214
	v_pk_mul_f32 v[66:67], v[66:67], v[214:215] op_sel_hi:[1,0]
	v_pk_mul_f32 v[68:69], v[68:69], v[214:215] op_sel_hi:[1,0]
	v_cvt_f32_u32_e32 v214, v213
	v_readfirstlane_b32 s29, v218
	v_add_f32_dpp v220, v212, v212 row_shr:1 row_mask:0xf bank_mask:0xf bound_ctrl:1
	v_fma_f32 v213, -v151, v214, v219
	v_mov_b32_e32 v218, v213
	v_add_f32_dpp v220, v220, v220 row_shr:2 row_mask:0xf bank_mask:0xf bound_ctrl:1
	s_nop 0
	v_max_f32_dpp v218, v213, v213 row_shr:1 row_mask:0xf bank_mask:0xf
	v_add_f32_dpp v220, v220, v220 row_shr:4 row_mask:0xf bank_mask:0xf bound_ctrl:1
	s_nop 0
	v_max_f32_dpp v218, v218, v218 row_shr:2 row_mask:0xf bank_mask:0xf
	v_add_f32_dpp v220, v220, v220 row_shr:8 row_mask:0xf bank_mask:0xf bound_ctrl:1
	s_nop 0
	v_max_f32_dpp v218, v218, v218 row_shr:4 row_mask:0xf bank_mask:0xf
	v_add_f32_dpp v157, v220, v220 row_bcast:15 row_mask:0xa bank_mask:0xf
	s_nop 0
	v_max_f32_dpp v218, v218, v218 row_shr:8 row_mask:0xf bank_mask:0xf
	v_mov_b32_dpp v158, v157 row_bcast:31 row_mask:0xc bank_mask:0xf
	s_nop 0
	v_max_f32_dpp v218, v218, v218 row_bcast:15 row_mask:0xa bank_mask:0xf
	s_nop 1
	v_max_f32_dpp v218, v218, v218 row_bcast:31 row_mask:0xc bank_mask:0xf
	v_max_f32_e64 v219, s30, s30
	v_readlane_b32 s0, v218, 63
	s_nop 1
	v_max_f32_e32 v218, s0, v219
	s_nop 0
	v_readfirstlane_b32 s28, v218
	s_nop 1
	v_subrev_f32_e32 v213, s28, v213
	v_exp_f32_e32 v213, v213
	v_mov_b32_e32 v218, s28
	v_sub_f32_e32 v218, s30, v218
	v_exp_f32_e32 v218, v218
	ds_write_b128 v137, v[210:213] offset:16384
	ds_read2st64_b32 v[210:211], v152 offset0:4 offset1:5
	v_add_f32_dpp v220, v213, v213 row_shr:1 row_mask:0xf bank_mask:0xf bound_ctrl:1
	v_mul_f32_e32 v219, v89, v218
	v_pk_mul_f32 v[78:79], v[78:79], v[218:219] op_sel_hi:[1,0]
	v_pk_mul_f32 v[80:81], v[80:81], v[218:219] op_sel_hi:[1,0]
	s_waitcnt lgkmcnt(0)
	v_fma_f32 v210, -v151, v216, v210
	v_mov_b32_e32 v212, v210
	v_fma_f32 v211, -v151, v217, v211
	s_nop 0
	v_max_f32_dpp v212, v210, v210 row_shr:1 row_mask:0xf bank_mask:0xf
	v_mov_b32_e32 v217, 0
	v_add_f32_dpp v220, v220, v220 row_shr:2 row_mask:0xf bank_mask:0xf bound_ctrl:1
	v_max_f32_dpp v212, v212, v212 row_shr:2 row_mask:0xf bank_mask:0xf
	s_nop 0
	v_add_f32_dpp v220, v220, v220 row_shr:4 row_mask:0xf bank_mask:0xf bound_ctrl:1
	v_readfirstlane_b32 s30, v219
	v_max_f32_dpp v212, v212, v212 row_shr:4 row_mask:0xf bank_mask:0xf
	v_add_f32_dpp v220, v220, v220 row_shr:8 row_mask:0xf bank_mask:0xf bound_ctrl:1
	s_nop 0
	v_max_f32_dpp v212, v212, v212 row_shr:8 row_mask:0xf bank_mask:0xf
	v_add_f32_dpp v159, v220, v220 row_bcast:15 row_mask:0xa bank_mask:0xf
	s_nop 0
	v_max_f32_dpp v212, v212, v212 row_bcast:15 row_mask:0xa bank_mask:0xf
	s_nop 0
	v_mov_b32_dpp v160, v159 row_bcast:31 row_mask:0xc bank_mask:0xf
	s_nop 0
	v_max_f32_dpp v212, v212, v212 row_bcast:31 row_mask:0xc bank_mask:0xf
	v_max_f32_e64 v213, s35, s35
	v_readlane_b32 s0, v212, 63
	s_nop 1
	v_max_f32_e32 v212, s0, v213
	s_nop 0
	v_readfirstlane_b32 s31, v212
	s_nop 1
	v_mov_b32_e32 v212, s31
	v_sub_f32_e32 v212, s35, v212
	v_exp_f32_e32 v212, v212
	v_subrev_f32_e32 v210, s31, v210
	v_exp_f32_e32 v210, v210
	v_mul_f32_e32 v213, v82, v212
	v_pk_mul_f32 v[54:55], v[54:55], v[212:213] op_sel_hi:[1,0]
	v_pk_mul_f32 v[56:57], v[56:57], v[212:213] op_sel_hi:[1,0]
	v_mov_b32_e32 v212, v211
	v_readfirstlane_b32 s35, v213
	v_add_f32_dpp v216, v210, v210 row_shr:1 row_mask:0xf bank_mask:0xf bound_ctrl:1
	v_max_f32_dpp v212, v211, v211 row_shr:1 row_mask:0xf bank_mask:0xf
	s_nop 0
	v_add_f32_dpp v216, v216, v216 row_shr:2 row_mask:0xf bank_mask:0xf bound_ctrl:1
	s_nop 0
	v_max_f32_dpp v212, v212, v212 row_shr:2 row_mask:0xf bank_mask:0xf
	v_add_f32_dpp v216, v216, v216 row_shr:4 row_mask:0xf bank_mask:0xf bound_ctrl:1
	s_nop 0
	v_max_f32_dpp v212, v212, v212 row_shr:4 row_mask:0xf bank_mask:0xf
	v_add_f32_dpp v216, v216, v216 row_shr:8 row_mask:0xf bank_mask:0xf bound_ctrl:1
	s_nop 0
	v_max_f32_dpp v212, v212, v212 row_shr:8 row_mask:0xf bank_mask:0xf
	v_add_f32_dpp v161, v216, v216 row_bcast:15 row_mask:0xa bank_mask:0xf
	s_nop 0
	v_max_f32_dpp v212, v212, v212 row_bcast:15 row_mask:0xa bank_mask:0xf
	v_mov_b32_dpp v162, v161 row_bcast:31 row_mask:0xc bank_mask:0xf
	s_nop 0
	v_max_f32_dpp v212, v212, v212 row_bcast:31 row_mask:0xc bank_mask:0xf
	v_max_f32_e64 v213, s42, s42
	v_readlane_b32 s0, v212, 63
	s_nop 1
	v_max_f32_e32 v212, s0, v213
	s_nop 0
	v_readfirstlane_b32 s34, v212
	s_nop 1
	v_mov_b32_e32 v212, s34
	v_sub_f32_e32 v212, s42, v212
	v_exp_f32_e32 v212, v212
	v_subrev_f32_e32 v211, s34, v211
	v_exp_f32_e32 v211, v211
	v_mul_f32_e32 v213, v83, v212
	s_nop 0
	v_readfirstlane_b32 s42, v213
	v_pk_mul_f32 v[62:63], v[62:63], v[212:213] op_sel_hi:[1,0]
	v_pk_mul_f32 v[64:65], v[64:65], v[212:213] op_sel_hi:[1,0]
	ds_read2st64_b32 v[212:213], v152 offset0:6 offset1:7
	v_add_f32_dpp v216, v211, v211 row_shr:1 row_mask:0xf bank_mask:0xf bound_ctrl:1
	s_waitcnt lgkmcnt(0)
; #define DPP_F(old, x, ctrl, rmask, bc) __builtin_bit_cast(float, __builtin_amdgcn_update_dpp(__builtin_bit_cast(int, (old)), __builtin_bit_cast(int, (x)), (ctrl), (rmask), 0xf, (bc)))
; __device__ __forceinline__ float wave_sum(float v) {
;     v += DPP_F(0.f, v, 0x111, 0xf, true); v += DPP_F(0.f, v, 0x112, 0xf, true); v += DPP_F(0.f, v, 0x114, 0xf, true); v += DPP_F(0.f, v, 0x118, 0xf, true);
;     v += DPP_F(0.f, v, 0x142, 0xa, false); v += DPP_F(0.f, v, 0x143, 0xc, false);
;     return __builtin_bit_cast(float, __builtin_amdgcn_readlane(__builtin_bit_cast(int, v), 63));
; }
; __device__ __forceinline__ float wave_max(float v) {
;     v = fmaxf(v, DPP_F(v, v, 0x111, 0xf, false)); v = fmaxf(v, DPP_F(v, v, 0x112, 0xf, false)); v = fmaxf(v, DPP_F(v, v, 0x114, 0xf, false)); v = fmaxf(v, DPP_F(v, v, 0x118, 0xf, false));
;     v = fmaxf(v, DPP_F(v, v, 0x142, 0xa, false)); v = fmaxf(v, DPP_F(v, v, 0x143, 0xc, false));
;     return __builtin_bit_cast(float, __builtin_amdgcn_readlane(__builtin_bit_cast(int, v), 63));
; }
; __device__ __forceinline__ void sattn_unit(const bf16* Qb, const bf16* Kb, const bf16* Vb, const float* ck, const float* cv, const int* pt, bf16* MIX, const float* sg, float lam,
;                                            int s, int h, int c0, LAS unsigned char* lds, int tid_in) {
;     ...
;         for (int c = 0; c < 8; ++c) { const int t = c & 3;
;             const float sv = sc[c * 64 + lane] - slope2 * (float)(PAST + t - (kp0 + lane));
;             const float mn = __builtin_bit_cast(float, __builtin_amdgcn_readfirstlane(__builtin_bit_cast(int, fmaxf(mrun[c], wave_max(sv))))); const float p = __builtin_amdgcn_exp2f(sv - mn);
;             const float fsc_ = __builtin_amdgcn_exp2f(mrun[c] - mn); lrun[c] = __builtin_bit_cast(float, __builtin_amdgcn_readfirstlane(__builtin_bit_cast(int, lrun[c] * fsc_ + wave_sum(p)))); mrun[c] = mn; pl[lane * 8 + c] = p; acc[c][0] *= fsc_; acc[c][1] *= fsc_; acc[c][2] *= fsc_; acc[c][3] *= fsc_; }
	v_fma_f32 v212, -v151, v215, v212
	v_add_f32_dpp v216, v216, v216 row_shr:2 row_mask:0xf bank_mask:0xf bound_ctrl:1
	v_mov_b32_e32 v215, v212
	v_fma_f32 v213, -v151, v214, v213
	v_add_f32_dpp v216, v216, v216 row_shr:4 row_mask:0xf bank_mask:0xf bound_ctrl:1
	s_nop 1
	v_add_f32_dpp v216, v216, v216 row_shr:8 row_mask:0xf bank_mask:0xf bound_ctrl:1
	v_max_f32_dpp v215, v212, v212 row_shr:1 row_mask:0xf bank_mask:0xf
	v_mov_b32_e32 v214, v213
	v_mov_b32_dpp v217, v216 row_bcast:15 row_mask:0xa bank_mask:0xf
	v_add_f32_e32 v163, v216, v217
	v_max_f32_dpp v215, v215, v215 row_shr:2 row_mask:0xf bank_mask:0xf
	v_max_f32_dpp v214, v213, v213 row_shr:1 row_mask:0xf bank_mask:0xf
	v_mov_b32_dpp v164, v163 row_bcast:31 row_mask:0xc bank_mask:0xf
	v_max_f32_dpp v215, v215, v215 row_shr:4 row_mask:0xf bank_mask:0xf
	s_nop 1
	v_max_f32_dpp v215, v215, v215 row_shr:8 row_mask:0xf bank_mask:0xf
	s_nop 1
	v_max_f32_dpp v215, v215, v215 row_bcast:15 row_mask:0xa bank_mask:0xf
	s_nop 1
	v_max_f32_dpp v215, v215, v215 row_bcast:31 row_mask:0xc bank_mask:0xf
	v_max_f32_e64 v216, s44, s44
	v_readlane_b32 s0, v215, 63
	s_nop 1
	v_max_f32_e32 v215, s0, v216
	s_nop 0
	v_readfirstlane_b32 s33, v215
	s_nop 1
	v_mov_b32_e32 v215, s33
	v_sub_f32_e32 v215, s44, v215
	v_exp_f32_e32 v216, v215
	v_subrev_f32_e32 v212, s33, v212
	v_exp_f32_e32 v212, v212
	v_mul_f32_e32 v215, v84, v216
	s_nop 0
	v_readfirstlane_b32 s44, v215
	v_add_f32_dpp v217, v212, v212 row_shr:1 row_mask:0xf bank_mask:0xf bound_ctrl:1
	s_nop 0
	v_max_f32_dpp v214, v214, v214 row_shr:2 row_mask:0xf bank_mask:0xf
	v_add_f32_dpp v217, v217, v217 row_shr:2 row_mask:0xf bank_mask:0xf bound_ctrl:1
	s_nop 0
	v_max_f32_dpp v214, v214, v214 row_shr:4 row_mask:0xf bank_mask:0xf
	v_add_f32_dpp v217, v217, v217 row_shr:4 row_mask:0xf bank_mask:0xf bound_ctrl:1
	s_nop 0
	v_max_f32_dpp v214, v214, v214 row_shr:8 row_mask:0xf bank_mask:0xf
	v_add_f32_dpp v217, v217, v217 row_shr:8 row_mask:0xf bank_mask:0xf bound_ctrl:1
	v_pk_mul_f32 v[74:75], v[74:75], v[216:217] op_sel_hi:[1,0]
	v_max_f32_dpp v214, v214, v214 row_bcast:15 row_mask:0xa bank_mask:0xf
	v_pk_mul_f32 v[76:77], v[76:77], v[216:217] op_sel_hi:[1,0]
	s_nop 0
	v_max_f32_dpp v214, v214, v214 row_bcast:31 row_mask:0xc bank_mask:0xf
	v_max_f32_e64 v215, s6, s6
	v_readlane_b32 s0, v214, 63
	v_add_f32_dpp v165, v217, v217 row_bcast:15 row_mask:0xa bank_mask:0xf
	s_nop 0
	v_max_f32_e32 v214, s0, v215
	v_mov_b32_dpp v166, v165 row_bcast:31 row_mask:0xc bank_mask:0xf
	v_readfirstlane_b32 s43, v214
	s_mov_b64 s[0:1], -1
	s_nop 0
	v_subrev_f32_e32 v213, s43, v213
	v_exp_f32_e32 v213, v213
	v_mov_b32_e32 v214, s43
	v_sub_f32_e32 v214, s6, v214
	v_exp_f32_e32 v214, v214
	v_add_f32_dpp v216, v213, v213 row_shr:1 row_mask:0xf bank_mask:0xf bound_ctrl:1
	ds_write_b128 v137, v[210:213] offset:16400
	s_waitcnt lgkmcnt(0)
	v_mul_f32_e32 v215, v85, v214
	v_add_f32_dpp v216, v216, v216 row_shr:2 row_mask:0xf bank_mask:0xf bound_ctrl:1
	v_readfirstlane_b32 s45, v215
	s_nop 0
	v_add_f32_dpp v216, v216, v216 row_shr:4 row_mask:0xf bank_mask:0xf bound_ctrl:1
	v_pk_mul_f32 v[70:71], v[70:71], v[214:215] op_sel_hi:[1,0]
	v_pk_mul_f32 v[72:73], v[72:73], v[214:215] op_sel_hi:[1,0]
	v_add_f32_dpp v216, v216, v216 row_shr:8 row_mask:0xf bank_mask:0xf bound_ctrl:1
	s_nop 0
	s_nop 0
	v_add_f32_dpp v167, v216, v216 row_bcast:15 row_mask:0xa bank_mask:0xf
	s_nop 1
	v_mov_b32_dpp v168, v167 row_bcast:31 row_mask:0xc bank_mask:0xf

; #define LAS __attribute__((address_space(3)))
; __device__ __forceinline__ void sattn_unit(const bf16* Qb, const bf16* Kb, const bf16* Vb, const float* ck, const float* cv, const int* pt, bf16* MIX, const float* sg, float lam,
;                                            int s, int h, int c0, LAS unsigned char* lds, int tid_in) {
;     ...
;         for (int k0 = 0; k0 < 64; k0 += 32) { f32x4 vv[16];
; #pragma unroll
;             for (int k = 0; k < 16; ++k) vv[k] = *(const f32x4*)(vp + (size_t)(k0 + 2 * k) * NH * 128);
;             asm volatile("" ::: "memory");
; #pragma unroll
;             for (int k = 0; k < 16; ++k) { const f32x4 v4 = vv[k]; const LAS float* pp = pl + (k0 + 2 * k + hi) * 8; const f32x4 p0 = *(const LAS f32x4*)pp, p1 = *(const LAS f32x4*)(pp + 4);
; #pragma unroll
;                 for (int c = 0; c < 4; ++c)
; #pragma unroll
;                     for (int i = 0; i < 4; ++i) { acc[c][i] += p0[c] * v4[i]; acc[4 + c][i] += p1[c] * v4[i]; } } }
.Lmy_sa_pvfma:
	ds_read_b128 v[170:173], v169 offset:16384
	ds_read_b128 v[174:177], v169 offset:16400
	ds_read_b128 v[178:181], v169 offset:16448
	ds_read_b128 v[182:185], v169 offset:16464
	ds_read_b128 v[186:189], v169 offset:16512
	ds_read_b128 v[190:193], v169 offset:16528
	ds_read_b128 v[194:197], v169 offset:16576
	ds_read_b128 v[198:201], v169 offset:16592
	ds_read_b128 v[202:205], v169 offset:16640
	ds_read_b128 v[206:209], v169 offset:16656
	s_mov_b32 s46, 32
	s_mov_b64 s[0:1], 0
	s_and_b64 vcc, exec, vcc
	s_waitcnt vmcnt(15) lgkmcnt(9)
	v_pk_fma_f32 v[66:67], v[110:111], v[172:173], v[66:67] op_sel_hi:[1,0,1]
	v_pk_fma_f32 v[50:51], v[110:111], v[170:171], v[50:51] op_sel_hi:[1,0,1]
	v_pk_fma_f32 v[52:53], v[112:113], v[170:171], v[52:53] op_sel_hi:[1,0,1]
	s_waitcnt vmcnt(14) lgkmcnt(7)
	v_pk_fma_f32 v[66:67], v[114:115], v[180:181], v[66:67] op_sel_hi:[1,0,1]
	v_pk_fma_f32 v[58:59], v[110:111], v[170:171], v[58:59] op_sel:[0,1,0]
	s_waitcnt vmcnt(13) lgkmcnt(5)
	v_pk_fma_f32 v[66:67], v[118:119], v[188:189], v[66:67] op_sel_hi:[1,0,1]
	v_pk_fma_f32 v[60:61], v[112:113], v[170:171], v[60:61] op_sel:[0,1,0]
	s_waitcnt lgkmcnt(3)
	v_mov_b32_e32 v170, v197
	v_pk_fma_f32 v[54:55], v[110:111], v[174:175], v[54:55] op_sel_hi:[1,0,1]
	s_waitcnt vmcnt(12)
	v_pk_fma_f32 v[66:67], v[122:123], v[196:197], v[66:67] op_sel_hi:[1,0,1]
	v_pk_fma_f32 v[62:63], v[110:111], v[174:175], v[62:63] op_sel:[0,1,0]
	s_waitcnt vmcnt(11) lgkmcnt(1)
	v_pk_fma_f32 v[226:227], v[126:127], v[204:205], v[66:67] op_sel_hi:[1,0,1]
	v_pk_fma_f32 v[66:67], v[110:111], v[176:177], v[74:75] op_sel_hi:[1,0,1]
	v_pk_fma_f32 v[50:51], v[114:115], v[178:179], v[50:51] op_sel_hi:[1,0,1]
	v_pk_fma_f32 v[66:67], v[114:115], v[184:185], v[66:67] op_sel_hi:[1,0,1]
	v_pk_fma_f32 v[54:55], v[114:115], v[182:183], v[54:55] op_sel_hi:[1,0,1]
	v_pk_fma_f32 v[66:67], v[118:119], v[192:193], v[66:67] op_sel_hi:[1,0,1]
	v_pk_fma_f32 v[58:59], v[114:115], v[178:179], v[58:59] op_sel:[0,1,0]
	v_pk_fma_f32 v[66:67], v[122:123], v[200:201], v[66:67] op_sel_hi:[1,0,1]
	v_pk_fma_f32 v[62:63], v[114:115], v[182:183], v[62:63] op_sel:[0,1,0]
	s_waitcnt lgkmcnt(0)
	v_pk_fma_f32 v[74:75], v[126:127], v[208:209], v[66:67] op_sel_hi:[1,0,1]
	v_pk_fma_f32 v[66:67], v[112:113], v[172:173], v[68:69] op_sel_hi:[1,0,1]
	v_mov_b32_e32 v172, v205
	v_pk_fma_f32 v[66:67], v[116:117], v[180:181], v[66:67] op_sel_hi:[1,0,1]
	v_pk_fma_f32 v[50:51], v[118:119], v[186:187], v[50:51] op_sel_hi:[1,0,1]
	v_pk_fma_f32 v[66:67], v[120:121], v[188:189], v[66:67] op_sel_hi:[1,0,1]
	v_pk_fma_f32 v[54:55], v[118:119], v[190:191], v[54:55] op_sel_hi:[1,0,1]
	v_pk_fma_f32 v[66:67], v[124:125], v[196:197], v[66:67] op_sel_hi:[1,0,1]
	v_pk_fma_f32 v[58:59], v[118:119], v[186:187], v[58:59] op_sel:[0,1,0]
	v_pk_fma_f32 v[228:229], v[128:129], v[204:205], v[66:67] op_sel_hi:[1,0,1]
	v_pk_fma_f32 v[66:67], v[112:113], v[176:177], v[76:77] op_sel_hi:[1,0,1]
	v_mov_b32_e32 v76, v181
	v_pk_fma_f32 v[66:67], v[116:117], v[184:185], v[66:67] op_sel_hi:[1,0,1]
	v_pk_fma_f32 v[62:63], v[118:119], v[190:191], v[62:63] op_sel:[0,1,0]
	v_pk_fma_f32 v[66:67], v[120:121], v[192:193], v[66:67] op_sel_hi:[1,0,1]
	v_pk_fma_f32 v[50:51], v[122:123], v[194:195], v[50:51] op_sel_hi:[1,0,1]
	v_pk_fma_f32 v[66:67], v[124:125], v[200:201], v[66:67] op_sel_hi:[1,0,1]
	v_pk_fma_f32 v[54:55], v[122:123], v[198:199], v[54:55] op_sel_hi:[1,0,1]
	v_pk_fma_f32 v[230:231], v[128:129], v[208:209], v[66:67] op_sel_hi:[1,0,1]
	v_mov_b32_e32 v66, v173
	v_pk_fma_f32 v[68:69], v[110:111], v[66:67], v[78:79] op_sel_hi:[1,0,1]
	v_mov_b32_e32 v78, v189
	v_pk_fma_f32 v[68:69], v[114:115], v[76:77], v[68:69] op_sel_hi:[1,0,1]
	v_pk_fma_f32 v[66:67], v[112:113], v[66:67], v[80:81] op_sel_hi:[1,0,1]
	v_pk_fma_f32 v[68:69], v[118:119], v[78:79], v[68:69] op_sel_hi:[1,0,1]
	v_pk_fma_f32 v[66:67], v[116:117], v[76:77], v[66:67] op_sel_hi:[1,0,1]
	v_pk_fma_f32 v[68:69], v[122:123], v[170:171], v[68:69] op_sel_hi:[1,0,1]
	v_pk_fma_f32 v[66:67], v[120:121], v[78:79], v[66:67] op_sel_hi:[1,0,1]
	v_pk_fma_f32 v[232:233], v[126:127], v[172:173], v[68:69] op_sel_hi:[1,0,1]
	v_mov_b32_e32 v68, v177
	v_pk_fma_f32 v[66:67], v[124:125], v[170:171], v[66:67] op_sel_hi:[1,0,1]
	v_pk_fma_f32 v[70:71], v[110:111], v[68:69], v[70:71] op_sel_hi:[1,0,1]
	v_mov_b32_e32 v110, v185
	v_pk_fma_f32 v[80:81], v[128:129], v[172:173], v[66:67] op_sel_hi:[1,0,1]
	v_pk_fma_f32 v[66:67], v[112:113], v[68:69], v[72:73] op_sel_hi:[1,0,1]
	v_pk_fma_f32 v[70:71], v[114:115], v[110:111], v[70:71] op_sel_hi:[1,0,1]
	v_mov_b32_e32 v114, v193
	v_pk_fma_f32 v[66:67], v[116:117], v[110:111], v[66:67] op_sel_hi:[1,0,1]
	v_pk_fma_f32 v[70:71], v[118:119], v[114:115], v[70:71] op_sel_hi:[1,0,1]
	v_mov_b32_e32 v118, v201
	v_pk_fma_f32 v[66:67], v[120:121], v[114:115], v[66:67] op_sel_hi:[1,0,1]
	v_pk_fma_f32 v[58:59], v[122:123], v[194:195], v[58:59] op_sel:[0,1,0]
	v_pk_fma_f32 v[62:63], v[122:123], v[198:199], v[62:63] op_sel:[0,1,0]
	v_pk_fma_f32 v[70:71], v[122:123], v[118:119], v[70:71] op_sel_hi:[1,0,1]
	v_mov_b32_e32 v122, v209
	v_pk_fma_f32 v[66:67], v[124:125], v[118:119], v[66:67] op_sel_hi:[1,0,1]
	v_pk_fma_f32 v[56:57], v[112:113], v[174:175], v[56:57] op_sel_hi:[1,0,1]
	v_pk_fma_f32 v[64:65], v[112:113], v[174:175], v[64:65] op_sel:[0,1,0]
	v_pk_fma_f32 v[234:235], v[126:127], v[122:123], v[70:71] op_sel_hi:[1,0,1]
	v_pk_fma_f32 v[236:237], v[128:129], v[122:123], v[66:67] op_sel_hi:[1,0,1]
	ds_read_b128 v[66:69], v169 offset:16704
	ds_read_b128 v[70:73], v169 offset:16720
	v_pk_fma_f32 v[56:57], v[116:117], v[182:183], v[56:57] op_sel_hi:[1,0,1]
	v_pk_fma_f32 v[64:65], v[116:117], v[182:183], v[64:65] op_sel:[0,1,0]
	v_pk_fma_f32 v[56:57], v[120:121], v[190:191], v[56:57] op_sel_hi:[1,0,1]
	v_pk_fma_f32 v[64:65], v[120:121], v[190:191], v[64:65] op_sel:[0,1,0]
	v_pk_fma_f32 v[52:53], v[116:117], v[178:179], v[52:53] op_sel_hi:[1,0,1]
	v_pk_fma_f32 v[56:57], v[124:125], v[198:199], v[56:57] op_sel_hi:[1,0,1]
	v_pk_fma_f32 v[60:61], v[116:117], v[178:179], v[60:61] op_sel:[0,1,0]
	v_pk_fma_f32 v[64:65], v[124:125], v[198:199], v[64:65] op_sel:[0,1,0]
	v_pk_fma_f32 v[54:55], v[126:127], v[206:207], v[54:55] op_sel_hi:[1,0,1]
	v_pk_fma_f32 v[52:53], v[120:121], v[186:187], v[52:53] op_sel_hi:[1,0,1]
	v_pk_fma_f32 v[56:57], v[128:129], v[206:207], v[56:57] op_sel_hi:[1,0,1]
	v_pk_fma_f32 v[62:63], v[126:127], v[206:207], v[62:63] op_sel:[0,1,0]
	v_pk_fma_f32 v[60:61], v[120:121], v[186:187], v[60:61] op_sel:[0,1,0]
	v_pk_fma_f32 v[64:65], v[128:129], v[206:207], v[64:65] op_sel:[0,1,0]
	v_pk_fma_f32 v[52:53], v[124:125], v[194:195], v[52:53] op_sel_hi:[1,0,1]
	v_pk_fma_f32 v[60:61], v[124:125], v[194:195], v[60:61] op_sel:[0,1,0]
	s_waitcnt vmcnt(10) lgkmcnt(0)
; #define LAS __attribute__((address_space(3)))
; __device__ __forceinline__ void sattn_unit(const bf16* Qb, const bf16* Kb, const bf16* Vb, const float* ck, const float* cv, const int* pt, bf16* MIX, const float* sg, float lam,
;                                            int s, int h, int c0, LAS unsigned char* lds, int tid_in) {
;     ...
;         for (int k0 = 0; k0 < 64; k0 += 32) { f32x4 vv[16];
; #pragma unroll
;             for (int k = 0; k < 16; ++k) vv[k] = *(const f32x4*)(vp + (size_t)(k0 + 2 * k) * NH * 128);
;             asm volatile("" ::: "memory");
; #pragma unroll
;             for (int k = 0; k < 16; ++k) { const f32x4 v4 = vv[k]; const LAS float* pp = pl + (k0 + 2 * k + hi) * 8; const f32x4 p0 = *(const LAS f32x4*)pp, p1 = *(const LAS f32x4*)(pp + 4);
; #pragma unroll
;                 for (int c = 0; c < 4; ++c)
; #pragma unroll
;                     for (int i = 0; i < 4; ++i) { acc[c][i] += p0[c] * v4[i]; acc[4 + c][i] += p1[c] * v4[i]; } } }
	v_pk_fma_f32 v[54:55], v[2:3], v[70:71], v[54:55] op_sel_hi:[1,0,1]
	v_pk_fma_f32 v[56:57], v[4:5], v[70:71], v[56:57] op_sel_hi:[1,0,1]
	v_pk_fma_f32 v[62:63], v[2:3], v[70:71], v[62:63] op_sel:[0,1,0]
	v_pk_fma_f32 v[64:65], v[4:5], v[70:71], v[64:65] op_sel:[0,1,0]
	v_pk_fma_f32 v[70:71], v[2:3], v[72:73], v[74:75] op_sel_hi:[1,0,1]
	v_pk_fma_f32 v[50:51], v[126:127], v[202:203], v[50:51] op_sel_hi:[1,0,1]
	v_pk_fma_f32 v[52:53], v[128:129], v[202:203], v[52:53] op_sel_hi:[1,0,1]
	v_pk_fma_f32 v[58:59], v[126:127], v[202:203], v[58:59] op_sel:[0,1,0]
	v_pk_fma_f32 v[60:61], v[128:129], v[202:203], v[60:61] op_sel:[0,1,0]
	ds_read_b128 v[76:79], v169 offset:16768
	ds_read_b128 v[110:113], v169 offset:16784
	ds_read_b128 v[114:117], v169 offset:16832
	ds_read_b128 v[118:121], v169 offset:16848
	ds_read_b128 v[122:125], v169 offset:16896
	ds_read_b128 v[126:129], v169 offset:16912
	ds_read_b128 v[170:173], v169 offset:16960
	ds_read_b128 v[174:177], v169 offset:16976
	ds_read_b128 v[178:181], v169 offset:17024
	ds_read_b128 v[182:185], v169 offset:17040
	ds_read_b128 v[186:189], v169 offset:17088
	ds_read_b128 v[190:193], v169 offset:17104
	ds_read_b128 v[194:197], v169 offset:17152
	ds_read_b128 v[198:201], v169 offset:17168
	ds_read_b128 v[202:205], v169 offset:17216
	ds_read_b128 v[206:209], v169 offset:17232
	ds_read_b128 v[210:213], v169 offset:17280
	ds_read_b128 v[214:217], v169 offset:17296
	ds_read_b128 v[218:221], v169 offset:17344
	ds_read_b128 v[222:225], v169 offset:17360
	s_waitcnt vmcnt(9) lgkmcnt(14)
	v_pk_fma_f32 v[70:71], v[6:7], v[112:113], v[70:71] op_sel_hi:[1,0,1]
	v_mov_b32_e32 v238, v69
	s_waitcnt vmcnt(8)
	v_pk_fma_f32 v[70:71], v[10:11], v[120:121], v[70:71] op_sel_hi:[1,0,1]
	v_mov_b32_e32 v240, v73
	s_waitcnt vmcnt(7)
	v_pk_fma_f32 v[70:71], v[14:15], v[128:129], v[70:71] op_sel_hi:[1,0,1]
	v_pk_fma_f32 v[50:51], v[2:3], v[66:67], v[50:51] op_sel_hi:[1,0,1]
	s_waitcnt vmcnt(6) lgkmcnt(12)
	v_pk_fma_f32 v[70:71], v[242:243], v[176:177], v[70:71] op_sel_hi:[1,0,1]
	v_pk_fma_f32 v[52:53], v[4:5], v[66:67], v[52:53] op_sel_hi:[1,0,1]
	s_waitcnt vmcnt(5) lgkmcnt(10)
	v_pk_fma_f32 v[70:71], v[248:249], v[184:185], v[70:71] op_sel_hi:[1,0,1]
	v_pk_fma_f32 v[58:59], v[2:3], v[66:67], v[58:59] op_sel:[0,1,0]
	s_waitcnt vmcnt(4) lgkmcnt(8)
	v_pk_fma_f32 v[70:71], v[90:91], v[192:193], v[70:71] op_sel_hi:[1,0,1]
	v_pk_fma_f32 v[60:61], v[4:5], v[66:67], v[60:61] op_sel:[0,1,0]
	s_waitcnt vmcnt(3) lgkmcnt(6)
	v_pk_fma_f32 v[70:71], v[94:95], v[200:201], v[70:71] op_sel_hi:[1,0,1]
	v_pk_fma_f32 v[50:51], v[6:7], v[76:77], v[50:51] op_sel_hi:[1,0,1]
	s_waitcnt vmcnt(2) lgkmcnt(4)
	v_pk_fma_f32 v[70:71], v[98:99], v[208:209], v[70:71] op_sel_hi:[1,0,1]
	v_pk_fma_f32 v[52:53], v[8:9], v[76:77], v[52:53] op_sel_hi:[1,0,1]
	s_waitcnt vmcnt(1) lgkmcnt(2)
	v_pk_fma_f32 v[70:71], v[102:103], v[216:217], v[70:71] op_sel_hi:[1,0,1]
	v_pk_fma_f32 v[58:59], v[6:7], v[76:77], v[58:59] op_sel:[0,1,0]
	s_waitcnt vmcnt(0) lgkmcnt(0)
	v_pk_fma_f32 v[74:75], v[106:107], v[224:225], v[70:71] op_sel_hi:[1,0,1]
	v_pk_fma_f32 v[70:71], v[4:5], v[72:73], v[230:231] op_sel_hi:[1,0,1]
	v_pk_fma_f32 v[60:61], v[8:9], v[76:77], v[60:61] op_sel:[0,1,0]
	v_pk_fma_f32 v[70:71], v[8:9], v[112:113], v[70:71] op_sel_hi:[1,0,1]
	v_pk_fma_f32 v[66:67], v[2:3], v[68:69], v[226:227] op_sel_hi:[1,0,1]
	v_pk_fma_f32 v[70:71], v[12:13], v[120:121], v[70:71] op_sel_hi:[1,0,1]
	v_mov_b32_e32 v72, v79
	v_pk_fma_f32 v[70:71], v[16:17], v[128:129], v[70:71] op_sel_hi:[1,0,1]
	v_mov_b32_e32 v128, v113
	v_pk_fma_f32 v[70:71], v[244:245], v[176:177], v[70:71] op_sel_hi:[1,0,1]
	v_pk_fma_f32 v[54:55], v[6:7], v[110:111], v[54:55] op_sel_hi:[1,0,1]
	v_pk_fma_f32 v[70:71], v[250:251], v[184:185], v[70:71] op_sel_hi:[1,0,1]
	v_pk_fma_f32 v[56:57], v[8:9], v[110:111], v[56:57] op_sel_hi:[1,0,1]
	v_pk_fma_f32 v[70:71], v[92:93], v[192:193], v[70:71] op_sel_hi:[1,0,1]
	v_pk_fma_f32 v[62:63], v[6:7], v[110:111], v[62:63] op_sel:[0,1,0]
	v_pk_fma_f32 v[70:71], v[96:97], v[200:201], v[70:71] op_sel_hi:[1,0,1]
	v_pk_fma_f32 v[64:65], v[8:9], v[110:111], v[64:65] op_sel:[0,1,0]
	v_pk_fma_f32 v[70:71], v[100:101], v[208:209], v[70:71] op_sel_hi:[1,0,1]
	v_pk_fma_f32 v[66:67], v[6:7], v[78:79], v[66:67] op_sel_hi:[1,0,1]
	v_pk_fma_f32 v[70:71], v[104:105], v[216:217], v[70:71] op_sel_hi:[1,0,1]
	v_mov_b32_e32 v110, v117
	v_pk_fma_f32 v[76:77], v[108:109], v[224:225], v[70:71] op_sel_hi:[1,0,1]
	v_pk_fma_f32 v[70:71], v[2:3], v[238:239], v[232:233] op_sel_hi:[1,0,1]
	v_pk_fma_f32 v[2:3], v[2:3], v[240:241], v[234:235] op_sel_hi:[1,0,1]
	v_pk_fma_f32 v[70:71], v[6:7], v[72:73], v[70:71] op_sel_hi:[1,0,1]
	v_pk_fma_f32 v[2:3], v[6:7], v[128:129], v[2:3] op_sel_hi:[1,0,1]
	v_mov_b32_e32 v6, v121
	v_pk_fma_f32 v[50:51], v[10:11], v[114:115], v[50:51] op_sel_hi:[1,0,1]
	v_pk_fma_f32 v[54:55], v[10:11], v[118:119], v[54:55] op_sel_hi:[1,0,1]
	v_pk_fma_f32 v[58:59], v[10:11], v[114:115], v[58:59] op_sel:[0,1,0]
	v_pk_fma_f32 v[62:63], v[10:11], v[118:119], v[62:63] op_sel:[0,1,0]
	v_pk_fma_f32 v[66:67], v[10:11], v[116:117], v[66:67] op_sel_hi:[1,0,1]
	v_pk_fma_f32 v[68:69], v[4:5], v[68:69], v[228:229] op_sel_hi:[1,0,1]
	v_pk_fma_f32 v[70:71], v[10:11], v[110:111], v[70:71] op_sel_hi:[1,0,1]
	v_mov_b32_e32 v112, v125
	v_pk_fma_f32 v[2:3], v[10:11], v[6:7], v[2:3] op_sel_hi:[1,0,1]
	v_mov_b32_e32 v10, v129
	v_pk_fma_f32 v[50:51], v[14:15], v[122:123], v[50:51] op_sel_hi:[1,0,1]
	v_pk_fma_f32 v[54:55], v[14:15], v[126:127], v[54:55] op_sel_hi:[1,0,1]
	v_pk_fma_f32 v[52:53], v[12:13], v[114:115], v[52:53] op_sel_hi:[1,0,1]
	v_pk_fma_f32 v[58:59], v[14:15], v[122:123], v[58:59] op_sel:[0,1,0]
; #define LAS __attribute__((address_space(3)))
; __device__ __forceinline__ void sattn_unit(const bf16* Qb, const bf16* Kb, const bf16* Vb, const float* ck, const float* cv, const int* pt, bf16* MIX, const float* sg, float lam,
;                                            int s, int h, int c0, LAS unsigned char* lds, int tid_in) {
;     ...
;         for (int k0 = 0; k0 < 64; k0 += 32) { f32x4 vv[16];
; #pragma unroll
;             for (int k = 0; k < 16; ++k) vv[k] = *(const f32x4*)(vp + (size_t)(k0 + 2 * k) * NH * 128);
;             asm volatile("" ::: "memory");
; #pragma unroll
;             for (int k = 0; k < 16; ++k) { const f32x4 v4 = vv[k]; const LAS float* pp = pl + (k0 + 2 * k + hi) * 8; const f32x4 p0 = *(const LAS f32x4*)pp, p1 = *(const LAS f32x4*)(pp + 4);
; #pragma unroll
;                 for (int c = 0; c < 4; ++c)
; #pragma unroll
;                     for (int i = 0; i < 4; ++i) { acc[c][i] += p0[c] * v4[i]; acc[4 + c][i] += p1[c] * v4[i]; } } }
	v_pk_fma_f32 v[62:63], v[14:15], v[126:127], v[62:63] op_sel:[0,1,0]
	v_pk_fma_f32 v[60:61], v[12:13], v[114:115], v[60:61] op_sel:[0,1,0]
	v_pk_fma_f32 v[66:67], v[14:15], v[124:125], v[66:67] op_sel_hi:[1,0,1]
	v_pk_fma_f32 v[68:69], v[8:9], v[78:79], v[68:69] op_sel_hi:[1,0,1]
	v_pk_fma_f32 v[70:71], v[14:15], v[112:113], v[70:71] op_sel_hi:[1,0,1]
	v_mov_b32_e32 v114, v173
	v_pk_fma_f32 v[2:3], v[14:15], v[10:11], v[2:3] op_sel_hi:[1,0,1]
	v_mov_b32_e32 v14, v177
	v_pk_fma_f32 v[50:51], v[242:243], v[170:171], v[50:51] op_sel_hi:[1,0,1]
	v_pk_fma_f32 v[54:55], v[242:243], v[174:175], v[54:55] op_sel_hi:[1,0,1]
	v_pk_fma_f32 v[58:59], v[242:243], v[170:171], v[58:59] op_sel:[0,1,0]
	v_pk_fma_f32 v[62:63], v[242:243], v[174:175], v[62:63] op_sel:[0,1,0]
	v_pk_fma_f32 v[66:67], v[242:243], v[172:173], v[66:67] op_sel_hi:[1,0,1]
	v_pk_fma_f32 v[68:69], v[12:13], v[116:117], v[68:69] op_sel_hi:[1,0,1]
	v_pk_fma_f32 v[70:71], v[242:243], v[114:115], v[70:71] op_sel_hi:[1,0,1]
	v_mov_b32_e32 v116, v181
	v_pk_fma_f32 v[2:3], v[242:243], v[14:15], v[2:3] op_sel_hi:[1,0,1]
	v_mov_b32_e32 v242, v185
	v_pk_fma_f32 v[50:51], v[248:249], v[178:179], v[50:51] op_sel_hi:[1,0,1]
	v_pk_fma_f32 v[54:55], v[248:249], v[182:183], v[54:55] op_sel_hi:[1,0,1]
	v_pk_fma_f32 v[56:57], v[12:13], v[118:119], v[56:57] op_sel_hi:[1,0,1]
	v_pk_fma_f32 v[58:59], v[248:249], v[178:179], v[58:59] op_sel:[0,1,0]
	v_pk_fma_f32 v[62:63], v[248:249], v[182:183], v[62:63] op_sel:[0,1,0]
	v_pk_fma_f32 v[64:65], v[12:13], v[118:119], v[64:65] op_sel:[0,1,0]
	v_pk_fma_f32 v[66:67], v[248:249], v[180:181], v[66:67] op_sel_hi:[1,0,1]
	v_pk_fma_f32 v[70:71], v[248:249], v[116:117], v[70:71] op_sel_hi:[1,0,1]
	v_mov_b32_e32 v118, v189
	v_pk_fma_f32 v[2:3], v[248:249], v[242:243], v[2:3] op_sel_hi:[1,0,1]
	v_mov_b32_e32 v248, v193
	v_pk_fma_f32 v[50:51], v[90:91], v[186:187], v[50:51] op_sel_hi:[1,0,1]
	v_pk_fma_f32 v[54:55], v[90:91], v[190:191], v[54:55] op_sel_hi:[1,0,1]
	v_pk_fma_f32 v[58:59], v[90:91], v[186:187], v[58:59] op_sel:[0,1,0]
	v_pk_fma_f32 v[62:63], v[90:91], v[190:191], v[62:63] op_sel:[0,1,0]
	v_pk_fma_f32 v[66:67], v[90:91], v[188:189], v[66:67] op_sel_hi:[1,0,1]
	v_pk_fma_f32 v[70:71], v[90:91], v[118:119], v[70:71] op_sel_hi:[1,0,1]
	v_mov_b32_e32 v120, v197
	v_pk_fma_f32 v[2:3], v[90:91], v[248:249], v[2:3] op_sel_hi:[1,0,1]
	v_mov_b32_e32 v90, v201
	v_pk_fma_f32 v[50:51], v[94:95], v[194:195], v[50:51] op_sel_hi:[1,0,1]
	v_pk_fma_f32 v[54:55], v[94:95], v[198:199], v[54:55] op_sel_hi:[1,0,1]
	v_pk_fma_f32 v[52:53], v[16:17], v[122:123], v[52:53] op_sel_hi:[1,0,1]
	v_pk_fma_f32 v[58:59], v[94:95], v[194:195], v[58:59] op_sel:[0,1,0]
	v_pk_fma_f32 v[62:63], v[94:95], v[198:199], v[62:63] op_sel:[0,1,0]
	v_pk_fma_f32 v[60:61], v[16:17], v[122:123], v[60:61] op_sel:[0,1,0]
	v_pk_fma_f32 v[66:67], v[94:95], v[196:197], v[66:67] op_sel_hi:[1,0,1]
	v_pk_fma_f32 v[70:71], v[94:95], v[120:121], v[70:71] op_sel_hi:[1,0,1]
	v_mov_b32_e32 v122, v205
	v_pk_fma_f32 v[2:3], v[94:95], v[90:91], v[2:3] op_sel_hi:[1,0,1]
	v_mov_b32_e32 v94, v209
	v_pk_fma_f32 v[50:51], v[98:99], v[202:203], v[50:51] op_sel_hi:[1,0,1]
	v_pk_fma_f32 v[54:55], v[98:99], v[206:207], v[54:55] op_sel_hi:[1,0,1]
	v_pk_fma_f32 v[58:59], v[98:99], v[202:203], v[58:59] op_sel:[0,1,0]
	v_pk_fma_f32 v[62:63], v[98:99], v[206:207], v[62:63] op_sel:[0,1,0]
	v_pk_fma_f32 v[66:67], v[98:99], v[204:205], v[66:67] op_sel_hi:[1,0,1]
	v_pk_fma_f32 v[68:69], v[16:17], v[124:125], v[68:69] op_sel_hi:[1,0,1]
	v_pk_fma_f32 v[70:71], v[98:99], v[122:123], v[70:71] op_sel_hi:[1,0,1]
	v_mov_b32_e32 v124, v213
	v_pk_fma_f32 v[2:3], v[98:99], v[94:95], v[2:3] op_sel_hi:[1,0,1]
	v_mov_b32_e32 v98, v217
	v_pk_fma_f32 v[50:51], v[102:103], v[210:211], v[50:51] op_sel_hi:[1,0,1]
	v_pk_fma_f32 v[54:55], v[102:103], v[214:215], v[54:55] op_sel_hi:[1,0,1]
	v_pk_fma_f32 v[56:57], v[16:17], v[126:127], v[56:57] op_sel_hi:[1,0,1]
	v_pk_fma_f32 v[58:59], v[102:103], v[210:211], v[58:59] op_sel:[0,1,0]
	v_pk_fma_f32 v[62:63], v[102:103], v[214:215], v[62:63] op_sel:[0,1,0]
	v_pk_fma_f32 v[64:65], v[16:17], v[126:127], v[64:65] op_sel:[0,1,0]
	v_pk_fma_f32 v[66:67], v[102:103], v[212:213], v[66:67] op_sel_hi:[1,0,1]
	v_pk_fma_f32 v[70:71], v[102:103], v[124:125], v[70:71] op_sel_hi:[1,0,1]
	v_mov_b32_e32 v126, v221
	v_pk_fma_f32 v[2:3], v[102:103], v[98:99], v[2:3] op_sel_hi:[1,0,1]
	v_mov_b32_e32 v102, v225
	v_pk_fma_f32 v[78:79], v[106:107], v[126:127], v[70:71] op_sel_hi:[1,0,1]
	v_pk_fma_f32 v[70:71], v[106:107], v[102:103], v[2:3] op_sel_hi:[1,0,1]
	v_pk_fma_f32 v[2:3], v[4:5], v[238:239], v[80:81] op_sel_hi:[1,0,1]
	v_pk_fma_f32 v[52:53], v[244:245], v[170:171], v[52:53] op_sel_hi:[1,0,1]
	v_pk_fma_f32 v[2:3], v[8:9], v[72:73], v[2:3] op_sel_hi:[1,0,1]
	v_pk_fma_f32 v[56:57], v[244:245], v[174:175], v[56:57] op_sel_hi:[1,0,1]
	v_pk_fma_f32 v[2:3], v[12:13], v[110:111], v[2:3] op_sel_hi:[1,0,1]
	v_pk_fma_f32 v[60:61], v[244:245], v[170:171], v[60:61] op_sel:[0,1,0]
	v_pk_fma_f32 v[2:3], v[16:17], v[112:113], v[2:3] op_sel_hi:[1,0,1]
; #define LAS __attribute__((address_space(3)))
; __device__ __forceinline__ void sattn_unit(const bf16* Qb, const bf16* Kb, const bf16* Vb, const float* ck, const float* cv, const int* pt, bf16* MIX, const float* sg, float lam,
;                                            int s, int h, int c0, LAS unsigned char* lds, int tid_in) {
;     ...
;     for (int chunk = c0 + w; chunk < 32; chunk += 8) {
;     ...
;             const float fsc_ = __builtin_amdgcn_exp2f(mrun[c] - mn); lrun[c] = __builtin_bit_cast(float, __builtin_amdgcn_readfirstlane(__builtin_bit_cast(int, lrun[c] * fsc_ + wave_sum(p)))); mrun[c] = mn; pl[lane * 8 + c] = p; acc[c][0] *= fsc_; acc[c][1] *= fsc_; acc[c][2] *= fsc_; acc[c][3] *= fsc_; }
;     ...
;             for (int k = 0; k < 16; ++k) { const f32x4 v4 = vv[k]; const LAS float* pp = pl + (k0 + 2 * k + hi) * 8; const f32x4 p0 = *(const LAS f32x4*)pp, p1 = *(const LAS f32x4*)(pp + 4);
; #pragma unroll
;                 for (int c = 0; c < 4; ++c)
; #pragma unroll
;                     for (int i = 0; i < 4; ++i) { acc[c][i] += p0[c] * v4[i]; acc[4 + c][i] += p1[c] * v4[i]; } } }
	v_pk_fma_f32 v[64:65], v[244:245], v[174:175], v[64:65] op_sel:[0,1,0]
	v_pk_fma_f32 v[2:3], v[244:245], v[114:115], v[2:3] op_sel_hi:[1,0,1]
	v_pk_fma_f32 v[68:69], v[244:245], v[172:173], v[68:69] op_sel_hi:[1,0,1]
	v_pk_fma_f32 v[2:3], v[250:251], v[116:117], v[2:3] op_sel_hi:[1,0,1]
	v_pk_fma_f32 v[52:53], v[250:251], v[178:179], v[52:53] op_sel_hi:[1,0,1]
	v_pk_fma_f32 v[2:3], v[92:93], v[118:119], v[2:3] op_sel_hi:[1,0,1]
	v_pk_fma_f32 v[56:57], v[250:251], v[182:183], v[56:57] op_sel_hi:[1,0,1]
	v_pk_fma_f32 v[2:3], v[96:97], v[120:121], v[2:3] op_sel_hi:[1,0,1]
	v_pk_fma_f32 v[60:61], v[250:251], v[178:179], v[60:61] op_sel:[0,1,0]
	v_pk_fma_f32 v[2:3], v[100:101], v[122:123], v[2:3] op_sel_hi:[1,0,1]
	v_pk_fma_f32 v[64:65], v[250:251], v[182:183], v[64:65] op_sel:[0,1,0]
	v_pk_fma_f32 v[2:3], v[104:105], v[124:125], v[2:3] op_sel_hi:[1,0,1]
	v_pk_fma_f32 v[68:69], v[250:251], v[180:181], v[68:69] op_sel_hi:[1,0,1]
	v_pk_fma_f32 v[80:81], v[108:109], v[126:127], v[2:3] op_sel_hi:[1,0,1]
	v_pk_fma_f32 v[2:3], v[4:5], v[240:241], v[236:237] op_sel_hi:[1,0,1]
	v_pk_fma_f32 v[52:53], v[92:93], v[186:187], v[52:53] op_sel_hi:[1,0,1]
	v_pk_fma_f32 v[2:3], v[8:9], v[128:129], v[2:3] op_sel_hi:[1,0,1]
	v_pk_fma_f32 v[56:57], v[92:93], v[190:191], v[56:57] op_sel_hi:[1,0,1]
	v_pk_fma_f32 v[2:3], v[12:13], v[6:7], v[2:3] op_sel_hi:[1,0,1]
	v_pk_fma_f32 v[60:61], v[92:93], v[186:187], v[60:61] op_sel:[0,1,0]
	v_pk_fma_f32 v[2:3], v[16:17], v[10:11], v[2:3] op_sel_hi:[1,0,1]
	v_pk_fma_f32 v[64:65], v[92:93], v[190:191], v[64:65] op_sel:[0,1,0]
	v_pk_fma_f32 v[2:3], v[244:245], v[14:15], v[2:3] op_sel_hi:[1,0,1]
	v_pk_fma_f32 v[68:69], v[92:93], v[188:189], v[68:69] op_sel_hi:[1,0,1]
	v_pk_fma_f32 v[2:3], v[250:251], v[242:243], v[2:3] op_sel_hi:[1,0,1]
	v_pk_fma_f32 v[52:53], v[96:97], v[194:195], v[52:53] op_sel_hi:[1,0,1]
	v_pk_fma_f32 v[2:3], v[92:93], v[248:249], v[2:3] op_sel_hi:[1,0,1]
	v_pk_fma_f32 v[56:57], v[96:97], v[198:199], v[56:57] op_sel_hi:[1,0,1]
	v_pk_fma_f32 v[60:61], v[96:97], v[194:195], v[60:61] op_sel:[0,1,0]
	v_pk_fma_f32 v[64:65], v[96:97], v[198:199], v[64:65] op_sel:[0,1,0]
	v_pk_fma_f32 v[68:69], v[96:97], v[196:197], v[68:69] op_sel_hi:[1,0,1]
	v_pk_fma_f32 v[2:3], v[96:97], v[90:91], v[2:3] op_sel_hi:[1,0,1]
	v_pk_fma_f32 v[52:53], v[100:101], v[202:203], v[52:53] op_sel_hi:[1,0,1]
	v_pk_fma_f32 v[56:57], v[100:101], v[206:207], v[56:57] op_sel_hi:[1,0,1]
	v_pk_fma_f32 v[60:61], v[100:101], v[202:203], v[60:61] op_sel:[0,1,0]
	v_pk_fma_f32 v[64:65], v[100:101], v[206:207], v[64:65] op_sel:[0,1,0]
	v_pk_fma_f32 v[68:69], v[100:101], v[204:205], v[68:69] op_sel_hi:[1,0,1]
	v_pk_fma_f32 v[2:3], v[100:101], v[94:95], v[2:3] op_sel_hi:[1,0,1]
	v_pk_fma_f32 v[52:53], v[104:105], v[210:211], v[52:53] op_sel_hi:[1,0,1]
	v_pk_fma_f32 v[56:57], v[104:105], v[214:215], v[56:57] op_sel_hi:[1,0,1]
	v_pk_fma_f32 v[60:61], v[104:105], v[210:211], v[60:61] op_sel:[0,1,0]
	v_pk_fma_f32 v[64:65], v[104:105], v[214:215], v[64:65] op_sel:[0,1,0]
	v_pk_fma_f32 v[68:69], v[104:105], v[212:213], v[68:69] op_sel_hi:[1,0,1]
	v_pk_fma_f32 v[2:3], v[104:105], v[98:99], v[2:3] op_sel_hi:[1,0,1]
	v_pk_fma_f32 v[50:51], v[106:107], v[218:219], v[50:51] op_sel_hi:[1,0,1]
	v_pk_fma_f32 v[54:55], v[106:107], v[222:223], v[54:55] op_sel_hi:[1,0,1]
	v_pk_fma_f32 v[52:53], v[108:109], v[218:219], v[52:53] op_sel_hi:[1,0,1]
	v_pk_fma_f32 v[56:57], v[108:109], v[222:223], v[56:57] op_sel_hi:[1,0,1]
	v_pk_fma_f32 v[58:59], v[106:107], v[218:219], v[58:59] op_sel:[0,1,0]
	v_pk_fma_f32 v[62:63], v[106:107], v[222:223], v[62:63] op_sel:[0,1,0]
	v_pk_fma_f32 v[60:61], v[108:109], v[218:219], v[60:61] op_sel:[0,1,0]
	v_pk_fma_f32 v[64:65], v[108:109], v[222:223], v[64:65] op_sel:[0,1,0]
	v_pk_fma_f32 v[66:67], v[106:107], v[220:221], v[66:67] op_sel_hi:[1,0,1]
	v_pk_fma_f32 v[68:69], v[108:109], v[220:221], v[68:69] op_sel_hi:[1,0,1]
	v_pk_fma_f32 v[72:73], v[108:109], v[102:103], v[2:3] op_sel_hi:[1,0,1]
	s_cbranch_vccz .LBB0_499
	v_add_f32_e32 v4, v157, v158
	v_add_f32_e32 v5, v159, v160
	v_readlane_b32 s0, v153, 63
	v_readlane_b32 s1, v155, 63
	v_mov_b32_e32 v2, s25
	v_mov_b32_e32 v3, s26
	v_add_f32_e32 v6, v161, v162
	v_add_f32_e32 v7, v163, v164
	v_pk_add_f32 v[86:87], s[0:1], v[2:3]
	v_readlane_b32 s0, v4, 63
	v_readlane_b32 s1, v5, 63
	v_mov_b32_e32 v2, s29
	v_mov_b32_e32 v3, s30
	v_add_f32_e32 v8, v165, v166
	v_add_f32_e32 v9, v167, v168
	v_pk_add_f32 v[88:89], s[0:1], v[2:3]
	v_readlane_b32 s0, v6, 63
	v_readlane_b32 s1, v7, 63
	v_mov_b32_e32 v2, s35
	v_mov_b32_e32 v3, s42
	s_waitcnt lgkmcnt(0)
	v_pk_add_f32 v[82:83], s[0:1], v[2:3]
	v_readlane_b32 s0, v8, 63
	v_readlane_b32 s1, v9, 63
	v_mov_b32_e32 v2, s44
	v_mov_b32_e32 v3, s45
	v_pk_add_f32 v[84:85], s[0:1], v[2:3]
	s_add_i32 s0, s20, 8
	s_cmp_gt_i32 s20, 23
	s_cbranch_scc1 .LBB0_503
	s_mov_b32 s25, s23
	s_mov_b32 s26, s24
	s_mov_b32 s29, s27
	s_mov_b32 s30, s28
	s_mov_b32 s35, s31
	s_mov_b32 s42, s34
	s_mov_b32 s44, s33
	s_mov_b32 s6, s43
	s_mov_b32 s20, s0
	s_branch .LBB0_490
